# combined candidate plus front-loaded LDS reads in the k-loop groups (two ds_read_b128 per MFMA slot in the first three slots of each group)
# baseline (speedup 1.0000x reference)
; #define MFMA(a, b, c) __builtin_amdgcn_mfma_f32_32x32x16_bf16((a), (b), (c), 0, 0, 0)
;     ...
;     auto issue_at = [&](int mm0, int nn0, int kt, int buf) {
;       char* lb = L0 + buf * BUFB;
; #pragma unroll
;       for (int i = 0; i < 4; ++i) {
;         const int seg = wv * 4 + i, row = seg * 8 + gl_row;
;         const int c = (lane & 7) ^ ((row >> 1) & 7);
;         const u16* ap = (kt < g.split) ? g.a0 + (size_t)(mm0 + row) * g.ld0 + kt * g.ks0 : g.a1 + (size_t)(mm0 + row) * g.ld1 + (kt - g.split) * 64;
;         __builtin_amdgcn_global_load_lds((const unsigned*)(ap + c * 8), (__attribute__((address_space(3))) unsigned*)(lb + seg * 1024 + lane * 16), 16, 0, 0);
;       }
; #pragma unroll
;       for (int i = 0; i < BN / 64; ++i) {
;         const int seg = wv * (BN / 64) + i, row = seg * 8 + gl_row;
;         const int c = (lane & 7) ^ ((row >> 1) & 7);
;         __builtin_amdgcn_global_load_lds((const unsigned*)(g.W + (size_t)(nn0 + row) * g.K + kt * 64 + c * 8),
;                                          (__attribute__((address_space(3))) unsigned*)(lb + 256 * 128 + seg * 1024 + lane * 16), 16, 0, 0);
;       }
;     };
;     auto issue = [&](int kt, int buf) { issue_at(m0, n0, kt, buf); };
;     auto compute2 = [&](int buf) {
;       const char* lb = L0 + buf * BUFB;
; #pragma unroll
;       for (int ks = 0; ks < 4; ++ks) {
;         const int c = ks * 2 + hh;
;         bf16x8 wf[2], xf[MI];
; #pragma unroll
;         for (int j = 0; j < 2; ++j) { const int r = wn * 64 + j * 32 + l32; wf[j] = *(const bf16x8*)(lb + 256 * 128 + r * 128 + ((c ^ ((r >> 1) & 7)) << 4)); }
; #pragma unroll
;         for (int i = 0; i < MI; ++i) { const int r = wm * (MI * 32) + i * 32 + l32; xf[i] = *(const bf16x8*)(lb + r * 128 + ((c ^ ((r >> 1) & 7)) << 4)); }
; #pragma unroll
;         for (int i = 0; i < MI; ++i) {
;           acc[i][0] = MFMA(wf[0], xf[i], acc[i][0]);
;           acc[i][1] = MFMA(wf[1], xf[i], acc[i][1]);
;         }
;       }
;     };
.Lgemm_prio_798:
	s_and_b32 s14, s11, 0x10000
	s_xor_b32 s15, s14, 0x10000
	s_add_i32 s15, s15, 0
	s_add_i32 s14, s14, 0
	v_add_u32_e32 v0, s14, v175
	v_add_u32_e32 v176, v0, v171
	v_add_u32_e32 v0, v0, v170
	ds_read_b128 v[200:203], v176 offset:32768
	ds_read_b128 v[204:207], v176 offset:36864
	ds_read_b128 v[208:211], v0
	ds_read_b128 v[212:215], v0 offset:4096
	ds_read_b128 v[216:219], v0 offset:8192
	ds_read_b128 v[220:223], v0 offset:12288
	s_add_i32 s64, s15, 0x8000
	s_add_i32 m0, s15, s60
	v_lshl_add_u64 v[176:177], v[152:153], 0, s[2:3]
	global_load_lds_dwordx4 v[176:177], off
	s_add_i32 m0, s15, s61
	v_lshl_add_u64 v[176:177], v[150:151], 0, s[2:3]
	global_load_lds_dwordx4 v[176:177], off
	s_add_i32 m0, s15, s62
	v_lshl_add_u64 v[176:177], v[148:149], 0, s[2:3]
	global_load_lds_dwordx4 v[176:177], off
	s_add_i32 m0, s15, s63
	v_lshl_add_u64 v[176:177], v[146:147], 0, s[2:3]
	global_load_lds_dwordx4 v[176:177], off
	s_add_i32 m0, s64, s60
	v_lshl_add_u64 v[176:177], v[144:145], 0, s[2:3]
	global_load_lds_dwordx4 v[176:177], off
	s_add_i32 m0, s64, s61
	v_lshl_add_u64 v[176:177], v[142:143], 0, s[2:3]
	global_load_lds_dwordx4 v[176:177], off
	s_add_i32 m0, s64, s62
	v_lshl_add_u64 v[176:177], v[140:141], 0, s[2:3]
	global_load_lds_dwordx4 v[176:177], off
	s_add_i32 m0, s64, s63
	v_lshl_add_u64 v[176:177], v[138:139], 0, s[2:3]
	global_load_lds_dwordx4 v[176:177], off
	v_add_u32_e32 v0, s14, v174
	v_add_u32_e32 v176, v0, v171
	v_add_u32_e32 v0, v0, v170
	s_waitcnt lgkmcnt(3)
	v_mfma_f32_32x32x16_bf16 v[114:129], v[200:203], v[208:211], 0
	s_add_i32 s11, s11, 0x10000
	s_add_u32 s2, s2, 0x80
	s_addc_u32 s3, s3, 0
	s_cmpk_eq_i32 s2, 0x780
	ds_read_b128 v[224:227], v176 offset:32768
	ds_read_b128 v[228:231], v176 offset:36864
	v_mfma_f32_32x32x16_bf16 v[98:113], v[204:207], v[208:211], 0
	ds_read_b128 v[232:235], v0
	ds_read_b128 v[240:243], v0 offset:4096
	s_waitcnt lgkmcnt(6)
	v_mfma_f32_32x32x16_bf16 v[82:97], v[200:203], v[212:215], 0
	ds_read_b128 v[244:247], v0 offset:8192
	ds_read_b128 v[248:251], v0 offset:12288
	v_mfma_f32_32x32x16_bf16 v[66:81], v[204:207], v[212:215], 0
	s_waitcnt lgkmcnt(7)
	v_mfma_f32_32x32x16_bf16 v[50:65], v[200:203], v[216:219], 0
	v_mfma_f32_32x32x16_bf16 v[34:49], v[204:207], v[216:219], 0
	s_waitcnt lgkmcnt(6)
	v_mfma_f32_32x32x16_bf16 v[18:33], v[200:203], v[220:223], 0
	v_mfma_f32_32x32x16_bf16 v[2:17], v[204:207], v[220:223], 0
	s_branch .Lgemm_g1_798

; #define MFMA(a, b, c) __builtin_amdgcn_mfma_f32_32x32x16_bf16((a), (b), (c), 0, 0, 0)
;     ...
;     auto compute2 = [&](int buf) {
;       const char* lb = L0 + buf * BUFB;
; #pragma unroll
;       for (int ks = 0; ks < 4; ++ks) {
;         const int c = ks * 2 + hh;
;         bf16x8 wf[2], xf[MI];
; #pragma unroll
;         for (int j = 0; j < 2; ++j) { const int r = wn * 64 + j * 32 + l32; wf[j] = *(const bf16x8*)(lb + 256 * 128 + r * 128 + ((c ^ ((r >> 1) & 7)) << 4)); }
; #pragma unroll
;         for (int i = 0; i < MI; ++i) { const int r = wm * (MI * 32) + i * 32 + l32; xf[i] = *(const bf16x8*)(lb + r * 128 + ((c ^ ((r >> 1) & 7)) << 4)); }
; #pragma unroll
;         for (int i = 0; i < MI; ++i) {
;           acc[i][0] = MFMA(wf[0], xf[i], acc[i][0]);
;           acc[i][1] = MFMA(wf[1], xf[i], acc[i][1]);
;         }
;       }
;     };
;     if (NBUF == 3) {
;       issue(0, 0);
;       if (nk > 1) { issue(1, 1); if (BN == 128) asm volatile("s_waitcnt vmcnt(6)" ::: "memory"); else asm volatile("s_waitcnt vmcnt(5)" ::: "memory"); }
;       else asm volatile("s_waitcnt vmcnt(0)" ::: "memory");
;       asm volatile("s_waitcnt lgkmcnt(0)" ::: "memory");
;       __builtin_amdgcn_s_barrier();
;       int buf = 0;
;       for (int kt = 0; kt < nk; ++kt) {
;         const int b2 = buf == 0 ? 2 : buf - 1;
;         if (kt + 2 < nk) issue(kt + 2, b2);
;         compute2(buf);
;         if (kt + 2 < nk) { if (BN == 128) asm volatile("s_waitcnt vmcnt(6)" ::: "memory"); else asm volatile("s_waitcnt vmcnt(5)" ::: "memory"); }
;         else asm volatile("s_waitcnt vmcnt(0)" ::: "memory");
;         asm volatile("s_waitcnt lgkmcnt(0)" ::: "memory");
;         __builtin_amdgcn_s_barrier();
;         buf = buf == 2 ? 0 : buf + 1;
;       }
;     } else {
;       if (!(chain & 1)) {
;         issue(0, 0);
;         asm volatile("s_waitcnt vmcnt(0)" ::: "memory");
;         __syncthreads();
;       }
;       for (int kt = 0; kt < nk; ++kt) {
;         const int buf = kt & 1;
;         if (kt + 1 < nk) issue(kt + 1, buf ^ 1);
;         else if (chain & 2) issue_at(nmt * 256, nnt * BN, 0, buf ^ 1);
;         compute2(buf);
;         asm volatile("s_waitcnt vmcnt(0)" ::: "memory");
;         __syncthreads();
;       }
.Lgemm_g1_798:
	v_add_u32_e32 v0, s14, v173
	v_add_u32_e32 v176, v0, v171
	v_add_u32_e32 v0, v0, v170
	s_waitcnt lgkmcnt(3)
	v_mfma_f32_32x32x16_bf16 v[114:129], v[224:227], v[232:235], v[114:129]
	ds_read_b128 v[200:203], v176 offset:32768
	ds_read_b128 v[204:207], v176 offset:36864
	v_mfma_f32_32x32x16_bf16 v[98:113], v[228:231], v[232:235], v[98:113]
	ds_read_b128 v[208:211], v0
	ds_read_b128 v[212:215], v0 offset:4096
	s_waitcnt lgkmcnt(6)
	v_mfma_f32_32x32x16_bf16 v[82:97], v[224:227], v[240:243], v[82:97]
	ds_read_b128 v[216:219], v0 offset:8192
	ds_read_b128 v[220:223], v0 offset:12288
	v_mfma_f32_32x32x16_bf16 v[66:81], v[228:231], v[240:243], v[66:81]
	s_waitcnt lgkmcnt(7)
	v_mfma_f32_32x32x16_bf16 v[50:65], v[224:227], v[244:247], v[50:65]
	v_mfma_f32_32x32x16_bf16 v[34:49], v[228:231], v[244:247], v[34:49]
	s_waitcnt lgkmcnt(6)
	v_mfma_f32_32x32x16_bf16 v[18:33], v[224:227], v[248:251], v[18:33]
	v_mfma_f32_32x32x16_bf16 v[2:17], v[228:231], v[248:251], v[2:17]
	v_add_u32_e32 v0, s14, v172
	v_add_u32_e32 v176, v0, v171
	v_add_u32_e32 v0, v0, v170
	s_waitcnt lgkmcnt(3)
	v_mfma_f32_32x32x16_bf16 v[114:129], v[200:203], v[208:211], v[114:129]
	ds_read_b128 v[224:227], v176 offset:32768
	ds_read_b128 v[228:231], v176 offset:36864
	v_mfma_f32_32x32x16_bf16 v[98:113], v[204:207], v[208:211], v[98:113]
	ds_read_b128 v[232:235], v0
	ds_read_b128 v[240:243], v0 offset:4096
	s_waitcnt lgkmcnt(6)
	v_mfma_f32_32x32x16_bf16 v[82:97], v[200:203], v[212:215], v[82:97]
	ds_read_b128 v[244:247], v0 offset:8192
	ds_read_b128 v[248:251], v0 offset:12288
	v_mfma_f32_32x32x16_bf16 v[66:81], v[204:207], v[212:215], v[66:81]
	s_waitcnt lgkmcnt(7)
	v_mfma_f32_32x32x16_bf16 v[50:65], v[200:203], v[216:219], v[50:65]
	v_mfma_f32_32x32x16_bf16 v[34:49], v[204:207], v[216:219], v[34:49]
	s_waitcnt lgkmcnt(6)
	v_mfma_f32_32x32x16_bf16 v[18:33], v[200:203], v[220:223], v[18:33]
	v_mfma_f32_32x32x16_bf16 v[2:17], v[204:207], v[220:223], v[2:17]
	s_waitcnt vmcnt(0)
	s_waitcnt vmcnt(0) lgkmcnt(0)
	s_barrier
	s_cbranch_scc1 .Lgemm_exit_798
	s_and_b32 s14, s11, 0x10000
	s_xor_b32 s15, s14, 0x10000
	s_add_i32 s15, s15, 0
	s_add_i32 s14, s14, 0
	v_add_u32_e32 v0, s14, v175
	v_add_u32_e32 v176, v0, v171
	v_add_u32_e32 v0, v0, v170
	ds_read_b128 v[200:203], v176 offset:32768
	ds_read_b128 v[204:207], v176 offset:36864
	ds_read_b128 v[208:211], v0
	ds_read_b128 v[212:215], v0 offset:4096
	ds_read_b128 v[216:219], v0 offset:8192
	ds_read_b128 v[220:223], v0 offset:12288
	v_mfma_f32_32x32x16_bf16 v[114:129], v[224:227], v[232:235], v[114:129]
	s_add_i32 s64, s15, 0x8000
	s_add_i32 m0, s15, s60
	v_lshl_add_u64 v[176:177], v[152:153], 0, s[2:3]
	global_load_lds_dwordx4 v[176:177], off
	v_mfma_f32_32x32x16_bf16 v[98:113], v[228:231], v[232:235], v[98:113]
	s_add_i32 m0, s15, s61
	v_lshl_add_u64 v[176:177], v[150:151], 0, s[2:3]
	global_load_lds_dwordx4 v[176:177], off
	s_add_i32 m0, s15, s62
	v_mfma_f32_32x32x16_bf16 v[82:97], v[224:227], v[240:243], v[82:97]
	v_lshl_add_u64 v[176:177], v[148:149], 0, s[2:3]
	global_load_lds_dwordx4 v[176:177], off
	s_add_i32 m0, s15, s63
	v_lshl_add_u64 v[176:177], v[146:147], 0, s[2:3]
	v_mfma_f32_32x32x16_bf16 v[66:81], v[228:231], v[240:243], v[66:81]
	global_load_lds_dwordx4 v[176:177], off
	s_add_i32 m0, s64, s60
	v_lshl_add_u64 v[176:177], v[144:145], 0, s[2:3]
	global_load_lds_dwordx4 v[176:177], off
	v_mfma_f32_32x32x16_bf16 v[50:65], v[224:227], v[244:247], v[50:65]
	s_add_i32 m0, s64, s61
	v_lshl_add_u64 v[176:177], v[142:143], 0, s[2:3]
	global_load_lds_dwordx4 v[176:177], off
	s_add_i32 m0, s64, s62
	v_mfma_f32_32x32x16_bf16 v[34:49], v[228:231], v[244:247], v[34:49]
	v_lshl_add_u64 v[176:177], v[140:141], 0, s[2:3]
	global_load_lds_dwordx4 v[176:177], off
	s_add_i32 m0, s64, s63
	v_lshl_add_u64 v[176:177], v[138:139], 0, s[2:3]
	v_mfma_f32_32x32x16_bf16 v[18:33], v[224:227], v[248:251], v[18:33]
	global_load_lds_dwordx4 v[176:177], off
	v_mfma_f32_32x32x16_bf16 v[2:17], v[228:231], v[248:251], v[2:17]
	s_branch .Lgemm_rot_798

; #define MFMA(a, b, c) __builtin_amdgcn_mfma_f32_32x32x16_bf16((a), (b), (c), 0, 0, 0)
;     ...
;     auto issue_at = [&](int mm0, int nn0, int kt, int buf) {
;       char* lb = L0 + buf * BUFB;
; #pragma unroll
;       for (int i = 0; i < 4; ++i) {
;         const int seg = wv * 4 + i, row = seg * 8 + gl_row;
;         const int c = (lane & 7) ^ ((row >> 1) & 7);
;         const u16* ap = (kt < g.split) ? g.a0 + (size_t)(mm0 + row) * g.ld0 + kt * g.ks0 : g.a1 + (size_t)(mm0 + row) * g.ld1 + (kt - g.split) * 64;
;         __builtin_amdgcn_global_load_lds((const unsigned*)(ap + c * 8), (__attribute__((address_space(3))) unsigned*)(lb + seg * 1024 + lane * 16), 16, 0, 0);
;       }
; #pragma unroll
;       for (int i = 0; i < BN / 64; ++i) {
;         const int seg = wv * (BN / 64) + i, row = seg * 8 + gl_row;
;         const int c = (lane & 7) ^ ((row >> 1) & 7);
;         __builtin_amdgcn_global_load_lds((const unsigned*)(g.W + (size_t)(nn0 + row) * g.K + kt * 64 + c * 8),
;                                          (__attribute__((address_space(3))) unsigned*)(lb + 256 * 128 + seg * 1024 + lane * 16), 16, 0, 0);
;       }
;     };
;     auto issue = [&](int kt, int buf) { issue_at(m0, n0, kt, buf); };
;     auto compute2 = [&](int buf) {
;       const char* lb = L0 + buf * BUFB;
; #pragma unroll
;       for (int ks = 0; ks < 4; ++ks) {
;         const int c = ks * 2 + hh;
;         bf16x8 wf[2], xf[MI];
; #pragma unroll
;         for (int j = 0; j < 2; ++j) { const int r = wn * 64 + j * 32 + l32; wf[j] = *(const bf16x8*)(lb + 256 * 128 + r * 128 + ((c ^ ((r >> 1) & 7)) << 4)); }
; #pragma unroll
;         for (int i = 0; i < MI; ++i) { const int r = wm * (MI * 32) + i * 32 + l32; xf[i] = *(const bf16x8*)(lb + r * 128 + ((c ^ ((r >> 1) & 7)) << 4)); }
; #pragma unroll
;         for (int i = 0; i < MI; ++i) {
;           acc[i][0] = MFMA(wf[0], xf[i], acc[i][0]);
;           acc[i][1] = MFMA(wf[1], xf[i], acc[i][1]);
;         }
;       }
;     };
.Lgemm_prio_1274:
	s_and_b32 s59, s56, 0x10000
	s_xor_b32 s60, s59, 0x10000
	s_add_i32 s57, s58, 1
	s_add_i32 s60, s60, 0
	s_cmp_lt_u32 s58, 21
	s_cselect_b64 vcc, -1, 0
	v_add_u32_e32 v233, s59, v201
	v_add_u32_e32 v230, v233, v175
	v_add_u32_e32 v234, v233, v174
	ds_read_b128 v[202:205], v230 offset:32768
	ds_read_b128 v[206:209], v230 offset:36864
	ds_read_b128 v[210:213], v234
	ds_read_b128 v[214:217], v234 offset:4096
	ds_read_b128 v[218:221], v234 offset:8192
	ds_read_b128 v[222:225], v234 offset:12288
	s_add_i32 s66, s60, 0x8000
	v_lshl_add_u64 v[226:227], v[160:161], 0, s[2:3]
	v_lshl_add_u64 v[228:229], v[144:145], 0, s[2:3]
	v_cndmask_b32_e32 v227, v229, v227, vcc
	v_cndmask_b32_e32 v226, v228, v226, vcc
	v_lshl_add_u64 v[226:227], v[0:1], 1, v[226:227]
	s_add_i32 m0, s60, s62
	v_lshl_add_u64 v[228:229], v[142:143], 0, s[2:3]
	global_load_lds_dwordx4 v[226:227], off
	v_lshl_add_u64 v[226:227], v[158:159], 0, s[2:3]
	v_cndmask_b32_e32 v227, v229, v227, vcc
	v_cndmask_b32_e32 v226, v228, v226, vcc
	v_lshl_add_u64 v[226:227], v[130:131], 1, v[226:227]
	s_add_i32 m0, s60, s63
	v_lshl_add_u64 v[228:229], v[140:141], 0, s[2:3]
	global_load_lds_dwordx4 v[226:227], off
	v_lshl_add_u64 v[226:227], v[156:157], 0, s[2:3]
	v_cndmask_b32_e32 v227, v229, v227, vcc
	v_cndmask_b32_e32 v226, v228, v226, vcc
	v_lshl_add_u64 v[226:227], v[132:133], 1, v[226:227]
	s_add_i32 m0, s60, s64
	v_lshl_add_u64 v[228:229], v[138:139], 0, s[2:3]
	global_load_lds_dwordx4 v[226:227], off
	v_lshl_add_u64 v[226:227], v[154:155], 0, s[2:3]
	v_cndmask_b32_e32 v226, v228, v226, vcc
	v_cndmask_b32_e32 v227, v229, v227, vcc
	s_add_i32 m0, s60, s65
	v_lshl_add_u64 v[226:227], v[134:135], 1, v[226:227]
	global_load_lds_dwordx4 v[226:227], off
	s_add_i32 m0, s66, s62
	v_lshl_add_u64 v[226:227], v[146:147], 0, s[2:3]
	global_load_lds_dwordx4 v[226:227], off
	s_add_i32 m0, s66, s63
	v_lshl_add_u64 v[226:227], v[148:149], 0, s[2:3]
	global_load_lds_dwordx4 v[226:227], off
	s_add_i32 m0, s66, s64
	v_lshl_add_u64 v[226:227], v[150:151], 0, s[2:3]
	global_load_lds_dwordx4 v[226:227], off
	v_lshl_add_u64 v[226:227], v[152:153], 0, s[2:3]
	s_add_i32 m0, s66, s65
	s_add_i32 s58, s59, 0
	global_load_lds_dwordx4 v[226:227], off
	v_add_u32_e32 v233, s59, v200
	v_add_u32_e32 v230, v233, v175
	v_add_u32_e32 v234, v233, v174
	s_waitcnt lgkmcnt(3)
	v_mfma_f32_32x32x16_bf16 v[114:129], v[202:205], v[210:213], 0
	s_add_u32 s2, s2, 0x80
	s_addc_u32 s3, s3, 0
	s_add_i32 s56, s56, 0x10000
	s_cmpk_eq_i32 s2, 0x1580
	s_mov_b32 s58, s57
	ds_read_b128 v[240:243], v230 offset:32768
	ds_read_b128 v[244:247], v230 offset:36864
	v_mfma_f32_32x32x16_bf16 v[98:113], v[206:209], v[210:213], 0
	ds_read_b128 v[248:251], v234
	s_waitcnt lgkmcnt(5)
	v_mfma_f32_32x32x16_bf16 v[82:97], v[202:205], v[214:217], 0
	v_mfma_f32_32x32x16_bf16 v[66:81], v[206:209], v[214:217], 0
	ds_read_b128 v[214:217], v234 offset:4096
	s_waitcnt lgkmcnt(5)
	v_mfma_f32_32x32x16_bf16 v[50:65], v[202:205], v[218:221], 0
	v_mfma_f32_32x32x16_bf16 v[34:49], v[206:209], v[218:221], 0
	ds_read_b128 v[218:221], v234 offset:8192
	s_waitcnt lgkmcnt(5)
	v_mfma_f32_32x32x16_bf16 v[18:33], v[202:205], v[222:225], 0
	v_mfma_f32_32x32x16_bf16 v[2:17], v[206:209], v[222:225], 0
	ds_read_b128 v[222:225], v234 offset:12288
	s_branch .Lgemm_g1_1274

; #define MFMA(a, b, c) __builtin_amdgcn_mfma_f32_32x32x16_bf16((a), (b), (c), 0, 0, 0)
;     ...
;     auto compute2 = [&](int buf) {
;       const char* lb = L0 + buf * BUFB;
; #pragma unroll
;       for (int ks = 0; ks < 4; ++ks) {
;         const int c = ks * 2 + hh;
;         bf16x8 wf[2], xf[MI];
; #pragma unroll
;         for (int j = 0; j < 2; ++j) { const int r = wn * 64 + j * 32 + l32; wf[j] = *(const bf16x8*)(lb + 256 * 128 + r * 128 + ((c ^ ((r >> 1) & 7)) << 4)); }
; #pragma unroll
;         for (int i = 0; i < MI; ++i) { const int r = wm * (MI * 32) + i * 32 + l32; xf[i] = *(const bf16x8*)(lb + r * 128 + ((c ^ ((r >> 1) & 7)) << 4)); }
; #pragma unroll
;         for (int i = 0; i < MI; ++i) {
;           acc[i][0] = MFMA(wf[0], xf[i], acc[i][0]);
;           acc[i][1] = MFMA(wf[1], xf[i], acc[i][1]);
;         }
;       }
;     };
;     if (NBUF == 3) {
;       issue(0, 0);
;       if (nk > 1) { issue(1, 1); if (BN == 128) asm volatile("s_waitcnt vmcnt(6)" ::: "memory"); else asm volatile("s_waitcnt vmcnt(5)" ::: "memory"); }
;       else asm volatile("s_waitcnt vmcnt(0)" ::: "memory");
;       asm volatile("s_waitcnt lgkmcnt(0)" ::: "memory");
;       __builtin_amdgcn_s_barrier();
;       int buf = 0;
;       for (int kt = 0; kt < nk; ++kt) {
;         const int b2 = buf == 0 ? 2 : buf - 1;
;         if (kt + 2 < nk) issue(kt + 2, b2);
;         compute2(buf);
;         if (kt + 2 < nk) { if (BN == 128) asm volatile("s_waitcnt vmcnt(6)" ::: "memory"); else asm volatile("s_waitcnt vmcnt(5)" ::: "memory"); }
;         else asm volatile("s_waitcnt vmcnt(0)" ::: "memory");
;         asm volatile("s_waitcnt lgkmcnt(0)" ::: "memory");
;         __builtin_amdgcn_s_barrier();
;         buf = buf == 2 ? 0 : buf + 1;
;       }
;     } else {
;       if (!(chain & 1)) {
;         issue(0, 0);
;         asm volatile("s_waitcnt vmcnt(0)" ::: "memory");
;         __syncthreads();
;       }
;       for (int kt = 0; kt < nk; ++kt) {
;         const int buf = kt & 1;
;         if (kt + 1 < nk) issue(kt + 1, buf ^ 1);
;         else if (chain & 2) issue_at(nmt * 256, nnt * BN, 0, buf ^ 1);
;         compute2(buf);
;         asm volatile("s_waitcnt vmcnt(0)" ::: "memory");
;         __syncthreads();
;       }
.Lgemm_g1_1274:
	v_add_u32_e32 v233, s59, v199
	v_add_u32_e32 v230, v233, v175
	v_add_u32_e32 v234, v233, v174
	s_waitcnt lgkmcnt(3)
	v_mfma_f32_32x32x16_bf16 v[114:129], v[240:243], v[248:251], v[114:129]
	ds_read_b128 v[202:205], v230 offset:32768
	ds_read_b128 v[206:209], v230 offset:36864
	v_mfma_f32_32x32x16_bf16 v[98:113], v[244:247], v[248:251], v[98:113]
	ds_read_b128 v[210:213], v234
	s_waitcnt lgkmcnt(5)
	v_mfma_f32_32x32x16_bf16 v[82:97], v[240:243], v[214:217], v[82:97]
	v_mfma_f32_32x32x16_bf16 v[66:81], v[244:247], v[214:217], v[66:81]
	ds_read_b128 v[214:217], v234 offset:4096
	s_waitcnt lgkmcnt(5)
	v_mfma_f32_32x32x16_bf16 v[50:65], v[240:243], v[218:221], v[50:65]
	v_mfma_f32_32x32x16_bf16 v[34:49], v[244:247], v[218:221], v[34:49]
	ds_read_b128 v[218:221], v234 offset:8192
	s_waitcnt lgkmcnt(5)
	v_mfma_f32_32x32x16_bf16 v[18:33], v[240:243], v[222:225], v[18:33]
	v_mfma_f32_32x32x16_bf16 v[2:17], v[244:247], v[222:225], v[2:17]
	ds_read_b128 v[222:225], v234 offset:12288
	v_add_u32_e32 v233, s59, v176
	v_add_u32_e32 v230, v233, v175
	v_add_u32_e32 v234, v233, v174
	s_waitcnt lgkmcnt(3)
	v_mfma_f32_32x32x16_bf16 v[114:129], v[202:205], v[210:213], v[114:129]
	ds_read_b128 v[240:243], v230 offset:32768
	ds_read_b128 v[244:247], v230 offset:36864
	v_mfma_f32_32x32x16_bf16 v[98:113], v[206:209], v[210:213], v[98:113]
	ds_read_b128 v[248:251], v234
	s_waitcnt lgkmcnt(5)
	v_mfma_f32_32x32x16_bf16 v[82:97], v[202:205], v[214:217], v[82:97]
	v_mfma_f32_32x32x16_bf16 v[66:81], v[206:209], v[214:217], v[66:81]
	ds_read_b128 v[214:217], v234 offset:4096
	s_waitcnt lgkmcnt(5)
	v_mfma_f32_32x32x16_bf16 v[50:65], v[202:205], v[218:221], v[50:65]
	v_mfma_f32_32x32x16_bf16 v[34:49], v[206:209], v[218:221], v[34:49]
	ds_read_b128 v[218:221], v234 offset:8192
	s_waitcnt lgkmcnt(5)
	v_mfma_f32_32x32x16_bf16 v[18:33], v[202:205], v[222:225], v[18:33]
	v_mfma_f32_32x32x16_bf16 v[2:17], v[206:209], v[222:225], v[2:17]
	ds_read_b128 v[222:225], v234 offset:12288
	s_waitcnt vmcnt(0)
	s_waitcnt vmcnt(0) lgkmcnt(0)
	s_barrier
	s_cbranch_scc1 .Lgemm_exit_1274
	s_and_b32 s59, s56, 0x10000
	s_xor_b32 s60, s59, 0x10000
	s_add_i32 s57, s58, 1
	s_add_i32 s60, s60, 0
	s_cmp_lt_u32 s58, 21
	s_cselect_b64 vcc, -1, 0
	v_add_u32_e32 v233, s59, v201
	v_add_u32_e32 v230, v233, v175
	v_add_u32_e32 v234, v233, v174
	ds_read_b128 v[202:205], v230 offset:32768
	ds_read_b128 v[206:209], v230 offset:36864
	ds_read_b128 v[210:213], v234
	v_mfma_f32_32x32x16_bf16 v[114:129], v[240:243], v[248:251], v[114:129]
	s_add_i32 s66, s60, 0x8000
	v_lshl_add_u64 v[226:227], v[160:161], 0, s[2:3]
	v_lshl_add_u64 v[228:229], v[144:145], 0, s[2:3]
	v_cndmask_b32_e32 v227, v229, v227, vcc
	v_cndmask_b32_e32 v226, v228, v226, vcc
	v_lshl_add_u64 v[226:227], v[0:1], 1, v[226:227]
	v_mfma_f32_32x32x16_bf16 v[98:113], v[244:247], v[248:251], v[98:113]
	s_add_i32 m0, s60, s62
	v_lshl_add_u64 v[228:229], v[142:143], 0, s[2:3]
	global_load_lds_dwordx4 v[226:227], off
	v_lshl_add_u64 v[226:227], v[158:159], 0, s[2:3]
	v_cndmask_b32_e32 v227, v229, v227, vcc
	v_cndmask_b32_e32 v226, v228, v226, vcc
	v_mfma_f32_32x32x16_bf16 v[82:97], v[240:243], v[214:217], v[82:97]
	v_lshl_add_u64 v[226:227], v[130:131], 1, v[226:227]
	s_add_i32 m0, s60, s63
	v_lshl_add_u64 v[228:229], v[140:141], 0, s[2:3]
	global_load_lds_dwordx4 v[226:227], off
	v_lshl_add_u64 v[226:227], v[156:157], 0, s[2:3]
	v_cndmask_b32_e32 v227, v229, v227, vcc
	v_mfma_f32_32x32x16_bf16 v[66:81], v[244:247], v[214:217], v[66:81]
	ds_read_b128 v[214:217], v234 offset:4096
	v_cndmask_b32_e32 v226, v228, v226, vcc
	v_lshl_add_u64 v[226:227], v[132:133], 1, v[226:227]
	s_add_i32 m0, s60, s64
	v_lshl_add_u64 v[228:229], v[138:139], 0, s[2:3]
	global_load_lds_dwordx4 v[226:227], off
	v_lshl_add_u64 v[226:227], v[154:155], 0, s[2:3]
	v_mfma_f32_32x32x16_bf16 v[50:65], v[240:243], v[218:221], v[50:65]
	v_cndmask_b32_e32 v226, v228, v226, vcc
	v_cndmask_b32_e32 v227, v229, v227, vcc
	s_add_i32 m0, s60, s65
	v_lshl_add_u64 v[226:227], v[134:135], 1, v[226:227]
	global_load_lds_dwordx4 v[226:227], off
	s_add_i32 m0, s66, s62
	v_mfma_f32_32x32x16_bf16 v[34:49], v[244:247], v[218:221], v[34:49]
	ds_read_b128 v[218:221], v234 offset:8192
	v_lshl_add_u64 v[226:227], v[146:147], 0, s[2:3]
	global_load_lds_dwordx4 v[226:227], off
	s_add_i32 m0, s66, s63
	v_lshl_add_u64 v[226:227], v[148:149], 0, s[2:3]
	global_load_lds_dwordx4 v[226:227], off
	s_add_i32 m0, s66, s64
	v_mfma_f32_32x32x16_bf16 v[18:33], v[240:243], v[222:225], v[18:33]
	v_lshl_add_u64 v[226:227], v[150:151], 0, s[2:3]
	global_load_lds_dwordx4 v[226:227], off
	v_lshl_add_u64 v[226:227], v[152:153], 0, s[2:3]
	s_add_i32 m0, s66, s65
	s_add_i32 s58, s59, 0
	global_load_lds_dwordx4 v[226:227], off
	v_mfma_f32_32x32x16_bf16 v[2:17], v[244:247], v[222:225], v[2:17]
	ds_read_b128 v[222:225], v234 offset:12288
	s_branch .Lgemm_rot_1274

; #define MFMA(a, b, c) __builtin_amdgcn_mfma_f32_32x32x16_bf16((a), (b), (c), 0, 0, 0)
;     ...
;     auto issue_at = [&](int mm0, int nn0, int kt, int buf) {
;       char* lb = L0 + buf * BUFB;
; #pragma unroll
;       for (int i = 0; i < 4; ++i) {
;         const int seg = wv * 4 + i, row = seg * 8 + gl_row;
;         const int c = (lane & 7) ^ ((row >> 1) & 7);
;         const u16* ap = (kt < g.split) ? g.a0 + (size_t)(mm0 + row) * g.ld0 + kt * g.ks0 : g.a1 + (size_t)(mm0 + row) * g.ld1 + (kt - g.split) * 64;
;         __builtin_amdgcn_global_load_lds((const unsigned*)(ap + c * 8), (__attribute__((address_space(3))) unsigned*)(lb + seg * 1024 + lane * 16), 16, 0, 0);
;       }
; #pragma unroll
;       for (int i = 0; i < BN / 64; ++i) {
;         const int seg = wv * (BN / 64) + i, row = seg * 8 + gl_row;
;         const int c = (lane & 7) ^ ((row >> 1) & 7);
;         __builtin_amdgcn_global_load_lds((const unsigned*)(g.W + (size_t)(nn0 + row) * g.K + kt * 64 + c * 8),
;                                          (__attribute__((address_space(3))) unsigned*)(lb + 256 * 128 + seg * 1024 + lane * 16), 16, 0, 0);
;       }
;     };
;     auto issue = [&](int kt, int buf) { issue_at(m0, n0, kt, buf); };
;     auto compute2 = [&](int buf) {
;       const char* lb = L0 + buf * BUFB;
; #pragma unroll
;       for (int ks = 0; ks < 4; ++ks) {
;         const int c = ks * 2 + hh;
;         bf16x8 wf[2], xf[MI];
; #pragma unroll
;         for (int j = 0; j < 2; ++j) { const int r = wn * 64 + j * 32 + l32; wf[j] = *(const bf16x8*)(lb + 256 * 128 + r * 128 + ((c ^ ((r >> 1) & 7)) << 4)); }
; #pragma unroll
;         for (int i = 0; i < MI; ++i) { const int r = wm * (MI * 32) + i * 32 + l32; xf[i] = *(const bf16x8*)(lb + r * 128 + ((c ^ ((r >> 1) & 7)) << 4)); }
; #pragma unroll
;         for (int i = 0; i < MI; ++i) {
;           acc[i][0] = MFMA(wf[0], xf[i], acc[i][0]);
;           acc[i][1] = MFMA(wf[1], xf[i], acc[i][1]);
;         }
;       }
;     };
.Lgemm_prio_1371:
	s_and_b32 s17, s16, 0x10000
	s_xor_b32 s43, s17, 0x10000
	s_add_i32 s43, s43, 0
	s_add_i32 s17, s17, 0
	v_add_u32_e32 v0, s17, v174
	v_add_u32_e32 v175, v0, v170
	v_add_u32_e32 v0, v0, v169
	ds_read_b128 v[200:203], v175 offset:32768
	ds_read_b128 v[204:207], v175 offset:36864
	ds_read_b128 v[208:211], v0
	ds_read_b128 v[212:215], v0 offset:4096
	ds_read_b128 v[216:219], v0 offset:8192
	ds_read_b128 v[220:223], v0 offset:12288
	s_add_i32 s64, s43, 0x8000
	s_add_i32 m0, s43, s60
	v_lshl_add_u64 v[176:177], v[152:153], 0, s[10:11]
	global_load_lds_dwordx4 v[176:177], off
	s_add_i32 m0, s43, s61
	v_lshl_add_u64 v[176:177], v[150:151], 0, s[10:11]
	global_load_lds_dwordx4 v[176:177], off
	s_add_i32 m0, s43, s62
	v_lshl_add_u64 v[176:177], v[148:149], 0, s[10:11]
	global_load_lds_dwordx4 v[176:177], off
	s_add_i32 m0, s43, s63
	v_lshl_add_u64 v[176:177], v[146:147], 0, s[10:11]
	global_load_lds_dwordx4 v[176:177], off
	s_add_i32 m0, s64, s60
	v_lshl_add_u64 v[176:177], v[144:145], 0, s[10:11]
	global_load_lds_dwordx4 v[176:177], off
	s_add_i32 m0, s64, s61
	v_lshl_add_u64 v[176:177], v[142:143], 0, s[10:11]
	global_load_lds_dwordx4 v[176:177], off
	s_add_i32 m0, s64, s62
	v_lshl_add_u64 v[176:177], v[140:141], 0, s[10:11]
	global_load_lds_dwordx4 v[176:177], off
	s_add_i32 m0, s64, s63
	v_lshl_add_u64 v[176:177], v[138:139], 0, s[10:11]
	global_load_lds_dwordx4 v[176:177], off
	v_add_u32_e32 v0, s17, v173
	v_add_u32_e32 v175, v0, v170
	v_add_u32_e32 v0, v0, v169
	s_waitcnt lgkmcnt(3)
	v_mfma_f32_32x32x16_bf16 v[114:129], v[200:203], v[208:211], 0
	s_add_i32 s16, s16, 0x10000
	s_add_u32 s10, s10, 0x80
	s_addc_u32 s11, s11, 0
	s_cmpk_eq_i32 s10, 0x780
	ds_read_b128 v[224:227], v175 offset:32768
	ds_read_b128 v[228:231], v175 offset:36864
	v_mfma_f32_32x32x16_bf16 v[98:113], v[204:207], v[208:211], 0
	ds_read_b128 v[232:235], v0
	ds_read_b128 v[240:243], v0 offset:4096
	s_waitcnt lgkmcnt(6)
	v_mfma_f32_32x32x16_bf16 v[82:97], v[200:203], v[212:215], 0
	ds_read_b128 v[244:247], v0 offset:8192
	ds_read_b128 v[248:251], v0 offset:12288
	v_mfma_f32_32x32x16_bf16 v[66:81], v[204:207], v[212:215], 0
	s_waitcnt lgkmcnt(7)
	v_mfma_f32_32x32x16_bf16 v[50:65], v[200:203], v[216:219], 0
	v_mfma_f32_32x32x16_bf16 v[34:49], v[204:207], v[216:219], 0
	s_waitcnt lgkmcnt(6)
	v_mfma_f32_32x32x16_bf16 v[18:33], v[200:203], v[220:223], 0
	v_mfma_f32_32x32x16_bf16 v[2:17], v[204:207], v[220:223], 0
	s_branch .Lgemm_g1_1371

; #define MFMA(a, b, c) __builtin_amdgcn_mfma_f32_32x32x16_bf16((a), (b), (c), 0, 0, 0)
;     ...
;     auto compute2 = [&](int buf) {
;       const char* lb = L0 + buf * BUFB;
; #pragma unroll
;       for (int ks = 0; ks < 4; ++ks) {
;         const int c = ks * 2 + hh;
;         bf16x8 wf[2], xf[MI];
; #pragma unroll
;         for (int j = 0; j < 2; ++j) { const int r = wn * 64 + j * 32 + l32; wf[j] = *(const bf16x8*)(lb + 256 * 128 + r * 128 + ((c ^ ((r >> 1) & 7)) << 4)); }
; #pragma unroll
;         for (int i = 0; i < MI; ++i) { const int r = wm * (MI * 32) + i * 32 + l32; xf[i] = *(const bf16x8*)(lb + r * 128 + ((c ^ ((r >> 1) & 7)) << 4)); }
; #pragma unroll
;         for (int i = 0; i < MI; ++i) {
;           acc[i][0] = MFMA(wf[0], xf[i], acc[i][0]);
;           acc[i][1] = MFMA(wf[1], xf[i], acc[i][1]);
;         }
;       }
;     };
;     if (NBUF == 3) {
;       issue(0, 0);
;       if (nk > 1) { issue(1, 1); if (BN == 128) asm volatile("s_waitcnt vmcnt(6)" ::: "memory"); else asm volatile("s_waitcnt vmcnt(5)" ::: "memory"); }
;       else asm volatile("s_waitcnt vmcnt(0)" ::: "memory");
;       asm volatile("s_waitcnt lgkmcnt(0)" ::: "memory");
;       __builtin_amdgcn_s_barrier();
;       int buf = 0;
;       for (int kt = 0; kt < nk; ++kt) {
;         const int b2 = buf == 0 ? 2 : buf - 1;
;         if (kt + 2 < nk) issue(kt + 2, b2);
;         compute2(buf);
;         if (kt + 2 < nk) { if (BN == 128) asm volatile("s_waitcnt vmcnt(6)" ::: "memory"); else asm volatile("s_waitcnt vmcnt(5)" ::: "memory"); }
;         else asm volatile("s_waitcnt vmcnt(0)" ::: "memory");
;         asm volatile("s_waitcnt lgkmcnt(0)" ::: "memory");
;         __builtin_amdgcn_s_barrier();
;         buf = buf == 2 ? 0 : buf + 1;
;       }
;     } else {
;       if (!(chain & 1)) {
;         issue(0, 0);
;         asm volatile("s_waitcnt vmcnt(0)" ::: "memory");
;         __syncthreads();
;       }
;       for (int kt = 0; kt < nk; ++kt) {
;         const int buf = kt & 1;
;         if (kt + 1 < nk) issue(kt + 1, buf ^ 1);
;         else if (chain & 2) issue_at(nmt * 256, nnt * BN, 0, buf ^ 1);
;         compute2(buf);
;         asm volatile("s_waitcnt vmcnt(0)" ::: "memory");
;         __syncthreads();
;       }
.Lgemm_g1_1371:
	v_add_u32_e32 v0, s17, v172
	v_add_u32_e32 v175, v0, v170
	v_add_u32_e32 v0, v0, v169
	s_waitcnt lgkmcnt(3)
	v_mfma_f32_32x32x16_bf16 v[114:129], v[224:227], v[232:235], v[114:129]
	ds_read_b128 v[200:203], v175 offset:32768
	ds_read_b128 v[204:207], v175 offset:36864
	v_mfma_f32_32x32x16_bf16 v[98:113], v[228:231], v[232:235], v[98:113]
	ds_read_b128 v[208:211], v0
	ds_read_b128 v[212:215], v0 offset:4096
	s_waitcnt lgkmcnt(6)
	v_mfma_f32_32x32x16_bf16 v[82:97], v[224:227], v[240:243], v[82:97]
	ds_read_b128 v[216:219], v0 offset:8192
	ds_read_b128 v[220:223], v0 offset:12288
	v_mfma_f32_32x32x16_bf16 v[66:81], v[228:231], v[240:243], v[66:81]
	s_waitcnt lgkmcnt(7)
	v_mfma_f32_32x32x16_bf16 v[50:65], v[224:227], v[244:247], v[50:65]
	v_mfma_f32_32x32x16_bf16 v[34:49], v[228:231], v[244:247], v[34:49]
	s_waitcnt lgkmcnt(6)
	v_mfma_f32_32x32x16_bf16 v[18:33], v[224:227], v[248:251], v[18:33]
	v_mfma_f32_32x32x16_bf16 v[2:17], v[228:231], v[248:251], v[2:17]
	v_add_u32_e32 v0, s17, v171
	v_add_u32_e32 v175, v0, v170
	v_add_u32_e32 v0, v0, v169
	s_waitcnt lgkmcnt(3)
	v_mfma_f32_32x32x16_bf16 v[114:129], v[200:203], v[208:211], v[114:129]
	ds_read_b128 v[224:227], v175 offset:32768
	ds_read_b128 v[228:231], v175 offset:36864
	v_mfma_f32_32x32x16_bf16 v[98:113], v[204:207], v[208:211], v[98:113]
	ds_read_b128 v[232:235], v0
	ds_read_b128 v[240:243], v0 offset:4096
	s_waitcnt lgkmcnt(6)
	v_mfma_f32_32x32x16_bf16 v[82:97], v[200:203], v[212:215], v[82:97]
	ds_read_b128 v[244:247], v0 offset:8192
	ds_read_b128 v[248:251], v0 offset:12288
	v_mfma_f32_32x32x16_bf16 v[66:81], v[204:207], v[212:215], v[66:81]
	s_waitcnt lgkmcnt(7)
	v_mfma_f32_32x32x16_bf16 v[50:65], v[200:203], v[216:219], v[50:65]
	v_mfma_f32_32x32x16_bf16 v[34:49], v[204:207], v[216:219], v[34:49]
	s_waitcnt lgkmcnt(6)
	v_mfma_f32_32x32x16_bf16 v[18:33], v[200:203], v[220:223], v[18:33]
	v_mfma_f32_32x32x16_bf16 v[2:17], v[204:207], v[220:223], v[2:17]
	s_waitcnt vmcnt(0)
	s_waitcnt vmcnt(0) lgkmcnt(0)
	s_barrier
	s_cbranch_scc1 .Lgemm_exit_1371
	s_and_b32 s17, s16, 0x10000
	s_xor_b32 s43, s17, 0x10000
	s_add_i32 s43, s43, 0
	s_add_i32 s17, s17, 0
	v_add_u32_e32 v0, s17, v174
	v_add_u32_e32 v175, v0, v170
	v_add_u32_e32 v0, v0, v169
	ds_read_b128 v[200:203], v175 offset:32768
	ds_read_b128 v[204:207], v175 offset:36864
	ds_read_b128 v[208:211], v0
	ds_read_b128 v[212:215], v0 offset:4096
	ds_read_b128 v[216:219], v0 offset:8192
	ds_read_b128 v[220:223], v0 offset:12288
	v_mfma_f32_32x32x16_bf16 v[114:129], v[224:227], v[232:235], v[114:129]
	s_add_i32 s64, s43, 0x8000
	s_add_i32 m0, s43, s60
	v_lshl_add_u64 v[176:177], v[152:153], 0, s[10:11]
	global_load_lds_dwordx4 v[176:177], off
	v_mfma_f32_32x32x16_bf16 v[98:113], v[228:231], v[232:235], v[98:113]
	s_add_i32 m0, s43, s61
	v_lshl_add_u64 v[176:177], v[150:151], 0, s[10:11]
	global_load_lds_dwordx4 v[176:177], off
	s_add_i32 m0, s43, s62
	v_mfma_f32_32x32x16_bf16 v[82:97], v[224:227], v[240:243], v[82:97]
	v_lshl_add_u64 v[176:177], v[148:149], 0, s[10:11]
	global_load_lds_dwordx4 v[176:177], off
	s_add_i32 m0, s43, s63
	v_lshl_add_u64 v[176:177], v[146:147], 0, s[10:11]
	v_mfma_f32_32x32x16_bf16 v[66:81], v[228:231], v[240:243], v[66:81]
	global_load_lds_dwordx4 v[176:177], off
	s_add_i32 m0, s64, s60
	v_lshl_add_u64 v[176:177], v[144:145], 0, s[10:11]
	global_load_lds_dwordx4 v[176:177], off
	v_mfma_f32_32x32x16_bf16 v[50:65], v[224:227], v[244:247], v[50:65]
	s_add_i32 m0, s64, s61
	v_lshl_add_u64 v[176:177], v[142:143], 0, s[10:11]
	global_load_lds_dwordx4 v[176:177], off
	s_add_i32 m0, s64, s62
	v_mfma_f32_32x32x16_bf16 v[34:49], v[228:231], v[244:247], v[34:49]
	v_lshl_add_u64 v[176:177], v[140:141], 0, s[10:11]
	global_load_lds_dwordx4 v[176:177], off
	s_add_i32 m0, s64, s63
	v_lshl_add_u64 v[176:177], v[138:139], 0, s[10:11]
	v_mfma_f32_32x32x16_bf16 v[18:33], v[224:227], v[248:251], v[18:33]
	global_load_lds_dwordx4 v[176:177], off
	v_mfma_f32_32x32x16_bf16 v[2:17], v[228:231], v[248:251], v[2:17]
	s_branch .Lgemm_rot_1371
